# hyena filter first hidden layer: 33 flt_w1 loads issued before the first wait (fully unrolled, same summation order)
# baseline (speedup 1.0000x reference)
.LBB0_372:
	s_mov_b64 s[10:11], 0x1000
	v_lshl_add_u64 v[182:183], v[16:17], 0, s[10:11]
	global_load_dword v120, v[16:17], off offset:-256
	global_load_dword v121, v[16:17], off
	global_load_dword v122, v[16:17], off offset:256
	global_load_dword v123, v[16:17], off offset:512
	global_load_dword v124, v[16:17], off offset:768
	global_load_dword v125, v[16:17], off offset:1024
	global_load_dword v126, v[16:17], off offset:1280
	global_load_dword v127, v[16:17], off offset:1536
	global_load_dword v128, v[16:17], off offset:1792
	global_load_dword v129, v[16:17], off offset:2048
	global_load_dword v130, v[16:17], off offset:2304
	global_load_dword v131, v[16:17], off offset:2560
	global_load_dword v132, v[16:17], off offset:2816
	global_load_dword v133, v[16:17], off offset:3072
	global_load_dword v134, v[16:17], off offset:3328
	global_load_dword v135, v[16:17], off offset:3584
	global_load_dword v136, v[182:183], off offset:-256
	global_load_dword v137, v[182:183], off
	global_load_dword v138, v[182:183], off offset:256
	global_load_dword v139, v[182:183], off offset:512
	global_load_dword v140, v[182:183], off offset:768
	global_load_dword v141, v[182:183], off offset:1024
	global_load_dword v142, v[182:183], off offset:1280
	global_load_dword v143, v[182:183], off offset:1536
	global_load_dword v144, v[182:183], off offset:1792
	global_load_dword v145, v[182:183], off offset:2048
	global_load_dword v146, v[182:183], off offset:2304
	global_load_dword v147, v[182:183], off offset:2560
	global_load_dword v148, v[182:183], off offset:2816
	global_load_dword v149, v[182:183], off offset:3072
	global_load_dword v150, v[182:183], off offset:3328
	global_load_dword v151, v[182:183], off offset:3584
	global_load_dword v152, v[182:183], off offset:3840
	ds_read2_b32 v[114:115], v20 offset1:1
	ds_read2_b32 v[116:117], v20 offset0:2 offset1:3
	ds_read2_b32 v[118:119], v20 offset0:4 offset1:5
	ds_read2_b32 v[154:155], v20 offset0:6 offset1:7
	ds_read2_b32 v[156:157], v20 offset0:8 offset1:9
	ds_read2_b32 v[158:159], v20 offset0:10 offset1:11
	ds_read2_b32 v[160:161], v20 offset0:12 offset1:13
	ds_read2_b32 v[162:163], v20 offset0:14 offset1:15
	ds_read2_b32 v[164:165], v20 offset0:16 offset1:17
	ds_read2_b32 v[166:167], v20 offset0:18 offset1:19
	ds_read2_b32 v[168:169], v20 offset0:20 offset1:21
	ds_read2_b32 v[170:171], v20 offset0:22 offset1:23
	ds_read2_b32 v[172:173], v20 offset0:24 offset1:25
	ds_read2_b32 v[174:175], v20 offset0:26 offset1:27
	ds_read2_b32 v[176:177], v20 offset0:28 offset1:29
	ds_read2_b32 v[178:179], v20 offset0:30 offset1:31
	ds_read_b32 v180, v20 offset:128
	s_waitcnt lgkmcnt(0)
	s_waitcnt vmcnt(32)
	v_fmac_f32_e32 v2, v114, v120
	s_waitcnt vmcnt(31)
	v_fmac_f32_e32 v2, v115, v121
	s_waitcnt vmcnt(30)
	v_fmac_f32_e32 v2, v116, v122
	s_waitcnt vmcnt(29)
	v_fmac_f32_e32 v2, v117, v123
	s_waitcnt vmcnt(28)
	v_fmac_f32_e32 v2, v118, v124
	s_waitcnt vmcnt(27)
	v_fmac_f32_e32 v2, v119, v125
	s_waitcnt vmcnt(26)
	v_fmac_f32_e32 v2, v154, v126
	s_waitcnt vmcnt(25)
	v_fmac_f32_e32 v2, v155, v127
	s_waitcnt vmcnt(24)
	v_fmac_f32_e32 v2, v156, v128
	s_waitcnt vmcnt(23)
	v_fmac_f32_e32 v2, v157, v129
	s_waitcnt vmcnt(22)
	v_fmac_f32_e32 v2, v158, v130
	s_waitcnt vmcnt(21)
	v_fmac_f32_e32 v2, v159, v131
	s_waitcnt vmcnt(20)
	v_fmac_f32_e32 v2, v160, v132
	s_waitcnt vmcnt(19)
	v_fmac_f32_e32 v2, v161, v133
	s_waitcnt vmcnt(18)
	v_fmac_f32_e32 v2, v162, v134
	s_waitcnt vmcnt(17)
	v_fmac_f32_e32 v2, v163, v135
	s_waitcnt vmcnt(16)
	v_fmac_f32_e32 v2, v164, v136
	s_waitcnt vmcnt(15)
	v_fmac_f32_e32 v2, v165, v137
	s_waitcnt vmcnt(14)
	v_fmac_f32_e32 v2, v166, v138
	s_waitcnt vmcnt(13)
	v_fmac_f32_e32 v2, v167, v139
	s_waitcnt vmcnt(12)
	v_fmac_f32_e32 v2, v168, v140
	s_waitcnt vmcnt(11)
	v_fmac_f32_e32 v2, v169, v141
	s_waitcnt vmcnt(10)
	v_fmac_f32_e32 v2, v170, v142
	s_waitcnt vmcnt(9)
	v_fmac_f32_e32 v2, v171, v143
	s_waitcnt vmcnt(8)
	v_fmac_f32_e32 v2, v172, v144
	s_waitcnt vmcnt(7)
	v_fmac_f32_e32 v2, v173, v145
	s_waitcnt vmcnt(6)
	v_fmac_f32_e32 v2, v174, v146
	s_waitcnt vmcnt(5)
	v_fmac_f32_e32 v2, v175, v147
	s_waitcnt vmcnt(4)
	v_fmac_f32_e32 v2, v176, v148
	s_waitcnt vmcnt(3)
	v_fmac_f32_e32 v2, v177, v149
	s_waitcnt vmcnt(2)
	v_fmac_f32_e32 v2, v178, v150
	s_waitcnt vmcnt(1)
	v_fmac_f32_e32 v2, v179, v151
	s_waitcnt vmcnt(0)
	v_fmac_f32_e32 v2, v180, v152
	v_mul_f32_e32 v16, v19, v2
	v_and_b32_e32 v17, 0x7fffffff, v16
	v_cmp_nlt_f32_e64 s[8:9], |v16|, s50
	s_and_saveexec_b64 s[10:11], s[8:9]
	s_xor_b64 s[28:29], exec, s[10:11]
	s_cbranch_execz .LBB0_375
	v_lshrrev_b32_e32 v2, 23, v17
	v_add_u32_e32 v2, 0xffffff88, v2
	v_cmp_lt_u32_e32 vcc, 63, v2
	s_nop 1
	v_cndmask_b32_e32 v22, 0, v43, vcc
	v_add_u32_e32 v2, v22, v2
	v_cmp_lt_u32_e64 s[8:9], 31, v2
	s_nop 1
	v_cndmask_b32_e64 v22, 0, v44, s[8:9]
	v_add_u32_e32 v2, v22, v2
	v_cmp_lt_u32_e64 s[10:11], 31, v2
	s_nop 1
	v_cndmask_b32_e64 v22, 0, v44, s[10:11]
	v_add_u32_e32 v47, v22, v2
	v_and_b32_e32 v2, 0x7fffff, v17
	v_or_b32_e32 v34, 0x800000, v2
	v_mad_u64_u32 v[22:23], s[12:13], v34, s51, 0
	v_mov_b32_e32 v2, v23
	v_mad_u64_u32 v[24:25], s[12:13], v34, s56, v[2:3]
	v_mov_b32_e32 v2, v25
	v_mad_u64_u32 v[26:27], s[12:13], v34, s57, v[2:3]
	v_mov_b32_e32 v2, v27
	v_mad_u64_u32 v[28:29], s[12:13], v34, s58, v[2:3]
	v_mov_b32_e32 v2, v29
	v_mad_u64_u32 v[30:31], s[12:13], v34, s59, v[2:3]
	v_mov_b32_e32 v2, v31
	v_mad_u64_u32 v[32:33], s[12:13], v34, s60, v[2:3]
	v_mov_b32_e32 v2, v33
	v_mad_u64_u32 v[34:35], s[12:13], v34, s61, v[2:3]
	v_cndmask_b32_e32 v23, v32, v28, vcc
	v_cndmask_b32_e32 v2, v34, v30, vcc
	v_cndmask_b32_e32 v27, v35, v32, vcc
	v_cndmask_b32_e64 v25, v2, v23, s[8:9]
	v_cndmask_b32_e64 v2, v27, v2, s[8:9]
	v_cndmask_b32_e32 v27, v30, v26, vcc
	v_cndmask_b32_e64 v23, v23, v27, s[8:9]
	v_cndmask_b32_e32 v24, v28, v24, vcc
	v_cndmask_b32_e64 v2, v2, v25, s[10:11]
	v_cndmask_b32_e64 v25, v25, v23, s[10:11]
	v_sub_u32_e32 v29, 32, v47
	v_cndmask_b32_e64 v27, v27, v24, s[8:9]
	v_alignbit_b32 v30, v2, v25, v29
	v_cmp_eq_u32_e64 s[12:13], 0, v47
	v_cndmask_b32_e64 v23, v23, v27, s[10:11]
	v_cndmask_b32_e32 v22, v26, v22, vcc
	v_cndmask_b32_e64 v2, v30, v2, s[12:13]
	v_alignbit_b32 v28, v25, v23, v29
	v_cndmask_b32_e64 v22, v24, v22, s[8:9]
	v_cndmask_b32_e64 v25, v28, v25, s[12:13]
	v_bfe_u32 v31, v2, 29, 1
	v_cndmask_b32_e64 v22, v27, v22, s[10:11]
	v_alignbit_b32 v28, v2, v25, 30
	v_sub_u32_e32 v32, 0, v31
	v_alignbit_b32 v24, v23, v22, v29
	v_xor_b32_e32 v28, v28, v32
	v_cndmask_b32_e64 v23, v24, v23, s[12:13]
	v_alignbit_b32 v24, v25, v23, 30
	v_ffbh_u32_e32 v25, v28
	v_min_u32_e32 v25, 32, v25
	v_alignbit_b32 v22, v23, v22, 30
	v_xor_b32_e32 v24, v24, v32
	v_sub_u32_e32 v26, 31, v25
	v_xor_b32_e32 v22, v22, v32
	v_alignbit_b32 v27, v28, v24, v26
	v_alignbit_b32 v22, v24, v22, v26
	v_alignbit_b32 v23, v27, v22, 9
	v_ffbh_u32_e32 v24, v23
	v_min_u32_e32 v24, 32, v24
	v_lshrrev_b32_e32 v30, 29, v2
	v_not_b32_e32 v26, v24
	v_alignbit_b32 v22, v23, v22, v26
	v_lshlrev_b32_e32 v23, 31, v30
	v_or_b32_e32 v26, 0x33000000, v23
	v_add_lshl_u32 v24, v24, v25, 23
	v_lshrrev_b32_e32 v22, 9, v22
	v_sub_u32_e32 v24, v26, v24
	v_or_b32_e32 v23, 0.5, v23
	v_lshlrev_b32_e32 v25, 23, v25
	v_or_b32_e32 v22, v24, v22
	v_lshrrev_b32_e32 v24, 9, v27
	v_sub_u32_e32 v23, v23, v25
	v_or_b32_e32 v23, v24, v23
	v_mul_f32_e32 v24, 0x3fc90fda, v23
	v_fma_f32 v25, v23, s62, -v24
	v_fmac_f32_e32 v25, 0x33a22168, v23
	v_fmac_f32_e32 v25, 0x3fc90fda, v22
	v_lshrrev_b32_e32 v2, 30, v2
	v_add_f32_e32 v22, v24, v25
	v_add_u32_e32 v2, v31, v2
